# removed compiler-inserted full vmcnt waits at the tail-GEMM and up-GEMM phase starts (address VGPR renamed; parameter DMA no longer blocks the first tile loads)
# baseline (speedup 1.0000x reference)
; #define PG8_LAS __attribute__((address_space(3)))
;     __device__ __forceinline__ void prefetch(const Unit& u, int par, int wid, int lane_) const {
;         (void)lane_; int lane; asm volatile("v_mbcnt_lo_u32_b32 %0, -1, 0\n\tv_mbcnt_hi_u32_b32 %0, -1, %0" : "=v"(lane));
;         if (wid < 4) { const int c = lane * 4; const float* sp = (wid < 3 ? cw + wid * 5632 : cb) + (c >> 7) * 2816 + u.pn * 128 + (c & 127);
;             __builtin_amdgcn_global_load_lds((const unsigned*)sp, (PG8_LAS unsigned*)(wl2 + par * 1024 + wid * 256), 16, 0, 0); }
;         else { int gr = a_row0 + u.pm * a_rstep + (wid - 4) * 64 + lane; gr = gr < 0 ? 0 : (gr < nrows ? gr : nrows - 1);
;             __builtin_amdgcn_global_load_lds((const unsigned*)(rs + gr), (PG8_LAS unsigned*)(rsl2 + par * 256 + (wid - 4) * 64), 4, 0, 0); }
; template <class Epi, class Sched, bool ALIGN_EPI = false, bool SP2 = false>
; __device__ __forceinline__ void gemm_phase(PG8_LAS unsigned char* lds, const Gemm g, const Sched& S, const Epi& E, int wid0) {
;     int tid_; asm volatile("v_mbcnt_lo_u32_b32 %0, -1, 0\n\tv_mbcnt_hi_u32_b32 %0, -1, %0" : "=v"(tid_)); tid_ += wid0 * 64;
;     const int tid = tid_, wid = __builtin_amdgcn_readfirstlane(tid >> 6), lane = tid & 63, wr = wid >> 2, wc = wid & 3, fr = lane & 15, fq = lane >> 4;
;     const int K = g.K, nt = K / BK, lda = g.lda, ldb = g.ldb;
;     unsigned voffA, voffB;
;     { int R, C; stage_rc(tid * 16, R, C); const int Rb = Epi::PERM ? ((R & ~31) + perm32(R & 31)) : R;
;         const int Ra = Epi::ROWPERM ? ((R & 64) | ((R & 15) << 2) | ((R >> 4) & 3)) : R;
;         voffA = (unsigned)(Ra * lda + C) * 2u; voffB = (unsigned)(Rb * ldb + C) * 2u; }
;     const size_t r64voffA = (size_t)64 * lda * 2, r64voffB = (size_t)64 * ldb * 2;
;     const size_t kstep = (size_t)(BK * 2);
;     const size_t hstepB = (size_t)HALF * ldb * 2, hstepA = (size_t)HALF * lda * 2;
;     const size_t tstepB = 2 * hstepB;
;     ...
;     const unsigned ldsw = (unsigned)wid * 1024u;
;     const int aoff = lds_byte(wr * 64 + fr, fq * 8), boff = lds_byte(wc * 32 + fr, fq * 8);
;     ...
;     Unit cur, nxt; int ui = 0;
;     if (!S.next(0, cur)) return;
;     f32x4 acc[2][2][4][2];
; #pragma unroll
;     for (int a = 0; a < 2; ++a)
; #pragma unroll
;         for (int b = 0; b < 2; ++b)
; #pragma unroll
;             for (int m = 0; m < 4; ++m)
; #pragma unroll
.LBB0_540:
	s_lshl_b32 s40, s59, 10
	s_andn2_b64 vcc, exec, s[2:3]
	s_mul_i32 s2, s59, 0x1600
	s_cbranch_vccnz .LBB0_542
	s_ashr_i32 s3, s2, 31
	s_lshl_b64 s[6:7], s[2:3], 2
	s_add_u32 s1, s44, s6
	s_addc_u32 s3, s48, s7
	s_cmp_eq_u32 s59, 3
	s_cselect_b32 s1, s45, s1
	v_mov_b32_e32 v4, s1
	v_lshrrev_b32_e32 v6, 5, v3
	s_movk_i32 s1, 0xb00
	s_cselect_b32 s3, s49, s3
	v_mul_lo_u32 v6, v6, s1
	v_mov_b32_e32 v5, s3
	v_ashrrev_i32_e32 v7, 31, v6
	s_lshl_b32 s6, s92, 7
	v_lshl_add_u64 v[4:5], v[6:7], 2, v[4:5]
	s_ashr_i32 s7, s6, 31
	v_lshlrev_b32_e32 v3, 4, v3
	v_lshl_add_u64 v[4:5], s[6:7], 2, v[4:5]
	v_and_b32_e32 v6, 0x1f0, v3
	v_mov_b32_e32 v7, v0
	s_add_i32 s1, s40, 0
	v_lshl_add_u64 v[4:5], v[4:5], 0, v[6:7]
	s_add_i32 m0, s1, 0x22400
	s_nop 0
	global_load_lds_dwordx4 v[4:5], off
.LBB0_542:
	v_ashrrev_i32_e32 v4, 31, v2
	v_lshrrev_b32_e32 v4, 26, v4
	v_lshlrev_b32_e32 v3, 4, v2
	v_add_u32_e32 v4, v2, v4
	v_bfe_i32 v2, v2, 27, 1
	v_lshrrev_b32_e32 v2, 22, v2
	v_add_u32_e32 v2, v3, v2
	v_and_b32_e32 v2, 0xfffffc00, v2
	v_sub_u32_e32 v2, v3, v2
	v_lshrrev_b32_e32 v3, 4, v2
	s_add_u32 s41, s4, 0x18f74000
	v_bitop3_b32 v2, v3, v2, 32 bitop3:0x6c
	s_addc_u32 s86, s5, 0
	s_mul_i32 s1, s12, 0xb00000
	v_ashrrev_i32_e32 v6, 6, v4
	v_ashrrev_i32_e32 v4, 31, v2
	s_add_u32 s1, s4, s1
	s_mul_hi_u32 s3, s12, 0xb00000
	v_lshrrev_b32_e32 v4, 26, v4
	s_addc_u32 s3, s5, s3
	v_add_u32_e32 v4, v2, v4
	s_add_u32 s23, s1, 0x400000
	v_lshlrev_b32_e32 v3, 3, v6
	v_ashrrev_i32_e32 v5, 6, v4
	v_and_b32_e32 v4, 0xc0, v4
	s_addc_u32 s16, s3, 0
	s_mul_i32 s3, s58, 0x7f000
	v_and_b32_e32 v3, -16, v3
	v_sub_u32_e32 v2, v2, v4
	v_mov_b32_e32 v4, 1
	s_mul_hi_i32 s1, s58, 0x7f000
	s_add_u32 s14, s41, s3
	v_add_u32_e32 v3, v5, v3
	v_lshlrev_b32_e32 v7, 5, v6
	v_ashrrev_i16_sdwa v2, v4, sext(v2) dst_sel:DWORD dst_unused:UNUSED_PAD src0_sel:DWORD src1_sel:BYTE_0
	s_addc_u32 s15, s86, s1
	v_and_b32_e32 v11, 32, v7
	v_bfe_i32 v7, v2, 0, 16
	v_lshlrev_b32_e32 v2, 1, v3
	v_lshrrev_b32_e32 v4, 2, v3
	v_and_b32_e32 v5, 3, v5
	s_mov_b32 s1, 0x1fffe0
	s_ashr_i32 s93, s92, 31
	v_and_b32_e32 v2, 24, v2
	v_and_b32_e32 v4, 4, v4
	v_and_or_b32 v5, v3, s1, v5
	s_lshl_b64 s[6:7], s[92:93], 19
	v_or3_b32 v2, v5, v4, v2
	v_lshlrev_b32_e32 v4, 2, v3
	s_add_u32 s46, s23, s6
	v_and_b32_e32 v8, 64, v3
	v_and_b32_e32 v9, 60, v4
	v_bfe_u32 v10, v3, 4, 2
	v_add_lshl_u32 v4, v11, v7, 1
	s_addc_u32 s47, s16, s7
	v_or3_b32 v3, v8, v9, v10
	v_lshl_add_u32 v204, v2, 11, v4
	v_mov_b32_e32 v205, v0
	s_add_i32 s17, s40, 0
	v_lshl_add_u32 v202, v3, 11, v4
	v_lshl_add_u64 v[2:3], s[46:47], 0, v[204:205]
	s_add_i32 m0, s17, 0x10000
	v_lshl_add_u64 v[4:5], v[2:3], 0, s[64:65]
	global_load_lds_dwordx4 v204, s[46:47]
	s_add_i32 m0, s17, 0x12000
	v_mov_b32_e32 v203, v0
	global_load_lds_dwordx4 v[4:5], off
	v_lshl_add_u64 v[4:5], v[2:3], 0, s[66:67]
	s_add_i32 m0, s17, 0x14000
	s_movk_i32 s6, 0xf000
	global_load_lds_dwordx4 v[4:5], off
	v_lshl_add_u64 v[4:5], v[2:3], 0, s[68:69]
	s_add_i32 m0, s17, 0x16000
	s_mov_b32 s7, -1
	global_load_lds_dwordx4 v[4:5], off
	v_lshl_add_u64 v[4:5], s[14:15], 0, v[202:203]
	v_lshl_add_u64 v[12:13], v[4:5], 0, s[6:7]
	s_mov_b32 m0, s17
	s_mov_b64 s[6:7], 0x1f000
	s_add_i32 s93, s17, 0x2000
	global_load_lds_dwordx4 v[12:13], off
	v_lshl_add_u64 v[12:13], v[4:5], 0, s[6:7]
	s_mov_b32 m0, s93
	s_mov_b64 s[6:7], 0x3f000
	s_add_i32 s20, s17, 0x4000
	global_load_lds_dwordx4 v[12:13], off
	v_lshl_add_u64 v[12:13], v[4:5], 0, s[6:7]
	s_mov_b32 m0, s20
	s_mov_b64 s[6:7], 0x5f000
	s_add_i32 s21, s17, 0x6000
	global_load_lds_dwordx4 v[12:13], off
	v_lshl_add_u64 v[12:13], v[4:5], 0, s[6:7]
	s_mov_b32 m0, s21
	s_ashr_i32 s1, s0, 8
	global_load_lds_dwordx4 v[12:13], off
	s_cmp_eq_u32 s1, 1
	s_cselect_b64 s[30:31], -1, 0
	s_cmp_lg_u32 s1, 1
	s_cbranch_scc1 .LBB0_544
	s_barrier

; #define PG8_STAGE(bufoff, gbase, voff) do { _Pragma("unroll") for (int _i = 0; _i < 2; ++_i) \
;         __builtin_amdgcn_global_load_lds((const unsigned*)((const char*)(gbase) + (size_t)_i * r64##voff + voff), (PG8_LAS unsigned*)(lds + (bufoff) + ldsw + _i * 8192), 16, 0, 0); } while (0)
; #define PG8_BAR __builtin_amdgcn_s_barrier()
; template <class Epi, class Sched, bool ALIGN_EPI = false, bool SP2 = false>
; __device__ __forceinline__ void gemm_phase(PG8_LAS unsigned char* lds, const Gemm g, const Sched& S, const Epi& E, int wid0) {
;     int tid_; asm volatile("v_mbcnt_lo_u32_b32 %0, -1, 0\n\tv_mbcnt_hi_u32_b32 %0, -1, %0" : "=v"(tid_)); tid_ += wid0 * 64;
;     const int tid = tid_, wid = __builtin_amdgcn_readfirstlane(tid >> 6), lane = tid & 63, wr = wid >> 2, wc = wid & 3, fr = lane & 15, fq = lane >> 4;
;     const int K = g.K, nt = K / BK, lda = g.lda, ldb = g.ldb;
;     unsigned voffA, voffB;
;     { int R, C; stage_rc(tid * 16, R, C); const int Rb = Epi::PERM ? ((R & ~31) + perm32(R & 31)) : R;
;         const int Ra = Epi::ROWPERM ? ((R & 64) | ((R & 15) << 2) | ((R >> 4) & 3)) : R;
;         voffA = (unsigned)(Ra * lda + C) * 2u; voffB = (unsigned)(Rb * ldb + C) * 2u; }
;     ...
;     const char* cA = PG8_APTR(cur); const char* cB = (const char*)g.Bt + (size_t)cur.pn * tstepB;
;     S.a_ready(cur);
;     if constexpr (Epi::PREFETCH) E.prefetch(cur, 0, wid, lane);
;     if constexpr (SP2) {
;         PG8_STAGE(PG8_SB(0, 0), cB, voffB); PG8_STAGE(PG8_SB(0, 1), cB + hstepB, voffB); PG8_STAGE(PG8_SA(0, 0), cA, voffA); PG8_STAGE(PG8_SA(0, 1), cA + hstepA, voffA);
;         if (wr == 1) PG8_BAR;
.LBB0_826:
	v_mbcnt_lo_u32_b32 v1, -1, 0
	v_mbcnt_hi_u32_b32 v1, -1, v1
	s_mov_b32 s8, 0x7fffffe0
	v_add_u32_e32 v2, s61, v1
	v_bfe_i32 v4, v2, 27, 1
	v_lshlrev_b32_e32 v3, 4, v2
	v_lshrrev_b32_e32 v4, 22, v4
	v_add_u32_e32 v4, v3, v4
	v_and_b32_e32 v4, 0xfffffc00, v4
	v_sub_u32_e32 v3, v3, v4
	v_lshrrev_b32_e32 v4, 4, v3
	s_waitcnt vmcnt(2)
	v_ashrrev_i32_e32 v6, 31, v2
	v_bitop3_b32 v3, v4, v3, 32 bitop3:0x6c
	v_lshrrev_b32_e32 v6, 26, v6
	v_readfirstlane_b32 s19, v2
	v_ashrrev_i32_e32 v4, 31, v3
	v_add_u32_e32 v2, v2, v6
	v_lshrrev_b32_e32 v4, 26, v4
	v_ashrrev_i32_e32 v2, 6, v2
	v_add_u32_e32 v4, v3, v4
	v_lshlrev_b32_e32 v6, 3, v2
	v_ashrrev_i32_e32 v5, 6, v4
	v_and_b32_e32 v6, -16, v6
	v_add_u32_e32 v6, v5, v6
	v_and_b32_e32 v5, 3, v5
	v_lshrrev_b32_e32 v7, 2, v6
	v_lshlrev_b32_e32 v8, 1, v6
	v_and_b32_e32 v4, 0xc0, v4
	v_and_or_b32 v5, v6, s8, v5
	v_and_b32_e32 v7, 4, v7
	v_and_b32_e32 v8, 24, v8
	v_lshlrev_b32_e32 v2, 5, v2
	v_sub_u32_e32 v3, v3, v4
	v_mov_b32_e32 v4, 1
	v_or3_b32 v5, v5, v7, v8
	v_and_b32_e32 v2, 32, v2
	v_ashrrev_i16_sdwa v3, v4, sext(v3) dst_sel:DWORD dst_unused:UNUSED_PAD src0_sel:DWORD src1_sel:BYTE_0
	s_ashr_i32 s21, s19, 6
	v_mul_lo_u32 v5, v5, s7
	v_add_u32_sdwa v2, v2, sext(v3) dst_sel:DWORD dst_unused:UNUSED_PAD src0_sel:DWORD src1_sel:WORD_0
	v_mul_lo_u32 v3, v6, s0
	s_lshl_b32 s7, s0, 16
	v_readlane_b32 s0, v255, 11
	s_ashr_i32 s15, s19, 8
	s_lshl_b32 s20, s21, 10
	s_mul_i32 s16, s16, s0
	s_add_u32 s8, s12, s16
	s_mul_i32 s10, s48, s0
	s_addc_u32 s9, s13, 0
	s_add_i32 s0, s20, 0
	v_add_lshl_u32 v130, v5, v2, 1
	s_add_i32 m0, s0, 0x10000
	v_mov_b32_e32 v131, v0
	global_load_lds_dwordx4 v130, s[8:9]
	s_add_i32 m0, s0, 0x12000
	s_add_u32 s1, s1, s7
	v_lshl_add_u64 v[6:7], s[8:9], 0, v[130:131]
	s_addc_u32 s11, s6, 0
	v_lshl_add_u64 v[8:9], v[6:7], 0, s[82:83]
	s_add_u32 s6, s8, s49
	global_load_lds_dwordx4 v[8:9], off
	s_addc_u32 s7, s9, 0
	s_add_i32 m0, s0, 0x14000
	v_add_lshl_u32 v132, v2, v3, 1
	global_load_lds_dwordx4 v130, s[6:7]
	s_add_i32 m0, s0, 0x16000
	v_lshl_add_u64 v[2:3], s[6:7], 0, v[130:131]
	s_add_u32 s10, s1, s10
	v_lshl_add_u64 v[4:5], v[2:3], 0, s[82:83]
	s_addc_u32 s11, s11, 0
	v_mov_b32_e32 v133, v0
	s_add_i32 s6, s0, 0x2000
	global_load_lds_dwordx4 v[4:5], off
	v_lshl_add_u64 v[12:13], s[10:11], 0, v[132:133]
	s_mov_b32 m0, s0
	s_add_u32 s12, s10, s60
	global_load_lds_dwordx4 v132, s[10:11]
	v_lshl_add_u64 v[10:11], v[12:13], 0, s[36:37]
	s_mov_b32 m0, s6
	s_addc_u32 s13, s11, 0
	s_add_i32 s7, s0, 0x4000
	global_load_lds_dwordx4 v[10:11], off
	s_mov_b32 m0, s7
	v_lshl_add_u64 v[134:135], s[12:13], 0, v[132:133]
	global_load_lds_dwordx4 v132, s[12:13]
	s_add_i32 s13, s0, 0x6000
	v_lshl_add_u64 v[136:137], v[134:135], 0, s[36:37]
	s_mov_b32 m0, s13
	s_cmp_lg_u32 s15, 1
	global_load_lds_dwordx4 v[136:137], off
	s_cbranch_scc1 .LBB0_828
	s_barrier
